# P10 K-loop: LDS fragment reads double-buffered too (address registers renamed out of the fragment quads)
# speedup vs baseline: 1.0450x; 1.0001x over previous
; #define MFMA(a, b, c) __builtin_amdgcn_mfma_f32_32x32x16_bf16((a), (b), (c), 0, 0, 0)
; #define G_BARRIER() { asm volatile("s_waitcnt vmcnt(0) lgkmcnt(0)" ::: "memory"); __builtin_amdgcn_s_barrier(); asm volatile("" ::: "memory"); }
;     ...
;         for (int kt = 0; kt < nk; ++kt) {
;             if (kt + 1 < nk) { G_DMA(kt + 1, (kt + 1) & 1); }
;             const unsigned char* sa = lds + (kt & 1) * 65536 + (wt * 32 * TB + r) * 128;
;             const unsigned char* sw = lds + (kt & 1) * 65536 + 32768 + (wf * 64 + r) * 128;
; #pragma unroll
;             for (int ks = 0; ks < 4; ++ks) {
;                 bf16x8 wfr[2], afr[TB];
; #pragma unroll
;                 for (int fb = 0; fb < 2; ++fb) wfr[fb] = *(const bf16x8*)(sw + fb * 4096 + koff[ks]);
; #pragma unroll
;                 for (int tb = 0; tb < TB; ++tb) afr[tb] = *(const bf16x8*)(sa + tb * 4096 + koff[ks]);
; #pragma unroll
;                 for (int fb = 0; fb < 2; ++fb)
; #pragma unroll
;                     for (int tb = 0; tb < TB; ++tb) acc[fb][tb] = MFMA(wfr[fb], afr[tb], acc[fb][tb]);
;             }
;             G_BARRIER();
;         }
.LBB0_1175:
	s_add_i32 s55, s53, 0x10000
	s_and_b32 s56, s55, 0x10000
	s_add_i32 s56, s45, s56
	s_mov_b32 m0, s56
	s_nop 0
	global_load_lds_dwordx4 v240, s[60:61]
	s_add_i32 m0, s56, 0x8000
	s_nop 0
	global_load_lds_dwordx4 v240, s[62:63]
	s_add_i32 m0, s56, 0x2000
	s_nop 0
	global_load_lds_dwordx4 v241, s[60:61]
	s_add_i32 m0, s56, 0xa000
	s_nop 0
	global_load_lds_dwordx4 v241, s[62:63]
	s_add_i32 m0, s56, 0x4000
	s_nop 0
	global_load_lds_dwordx4 v242, s[60:61]
	s_add_i32 m0, s56, 0xc000
	s_nop 0
	global_load_lds_dwordx4 v242, s[62:63]
	s_add_i32 m0, s56, 0x6000
	s_nop 0
	global_load_lds_dwordx4 v243, s[60:61]
	s_add_i32 m0, s56, 0xe000
	s_and_b32 s53, s53, 0x10000
	s_nop 0
	global_load_lds_dwordx4 v243, s[62:63]
	s_add_u32 s60, s60, 0x80
	s_addc_u32 s61, s61, 0
	s_add_u32 s62, s62, 0x80
	s_addc_u32 s63, s63, 0
	s_add_i32 s53, s53, 16
	v_add3_u32 v149, s53, v184, v185
	v_add3_u32 v192, s53, v186, v185
	v_add_u32_e32 v228, v192, v179
	v_add_u32_e32 v229, v149, v179
	ds_read_b128 v[154:157], v228 offset:32768
	ds_read_b128 v[158:161], v229
	ds_read_b128 v[162:165], v228 offset:36864
	ds_read_b128 v[166:169], v229 offset:4096
	ds_read_b128 v[170:173], v229 offset:8192
	ds_read_b128 v[174:177], v229 offset:12288
	v_add_u32_e32 v193, v149, v180
	v_add_u32_e32 v230, v192, v180
	ds_read_b128 v[204:207], v230 offset:32768
	ds_read_b128 v[208:211], v193
	ds_read_b128 v[212:215], v230 offset:36864
	ds_read_b128 v[216:219], v193 offset:4096
	ds_read_b128 v[220:223], v193 offset:8192
	ds_read_b128 v[224:227], v193 offset:12288
	s_waitcnt lgkmcnt(6)
	v_mfma_f32_32x32x16_bf16 v[112:127], v[154:157], v[158:161], v[112:127]
	s_add_u32 s42, s42, 0x80
	s_addc_u32 s43, s43, 0
	s_cmpk_eq_i32 s42, 0x780
	s_mov_b32 s53, s55
	v_mfma_f32_32x32x16_bf16 v[96:111], v[154:157], v[166:169], v[96:111]
	v_mfma_f32_32x32x16_bf16 v[80:95], v[154:157], v[170:173], v[80:95]
	v_mfma_f32_32x32x16_bf16 v[64:79], v[154:157], v[174:177], v[64:79]
	v_mfma_f32_32x32x16_bf16 v[48:63], v[162:165], v[158:161], v[48:63]
	v_mfma_f32_32x32x16_bf16 v[32:47], v[162:165], v[166:169], v[32:47]
	v_mfma_f32_32x32x16_bf16 v[16:31], v[162:165], v[170:173], v[16:31]
	v_mfma_f32_32x32x16_bf16 v[0:15], v[162:165], v[174:177], v[0:15]
	v_add_u32_e32 v193, v149, v181
	v_add_u32_e32 v230, v192, v181
	ds_read_b128 v[154:157], v230 offset:32768
	ds_read_b128 v[158:161], v193
	ds_read_b128 v[162:165], v230 offset:36864
	ds_read_b128 v[166:169], v193 offset:4096
	ds_read_b128 v[170:173], v193 offset:8192
	ds_read_b128 v[174:177], v193 offset:12288
	s_waitcnt lgkmcnt(6)
	v_mfma_f32_32x32x16_bf16 v[112:127], v[204:207], v[208:211], v[112:127]
	v_mfma_f32_32x32x16_bf16 v[96:111], v[204:207], v[216:219], v[96:111]
	v_mfma_f32_32x32x16_bf16 v[80:95], v[204:207], v[220:223], v[80:95]
	v_mfma_f32_32x32x16_bf16 v[64:79], v[204:207], v[224:227], v[64:79]
	v_mfma_f32_32x32x16_bf16 v[48:63], v[212:215], v[208:211], v[48:63]
	v_mfma_f32_32x32x16_bf16 v[32:47], v[212:215], v[216:219], v[32:47]
	v_mfma_f32_32x32x16_bf16 v[16:31], v[212:215], v[220:223], v[16:31]
	v_mfma_f32_32x32x16_bf16 v[0:15], v[212:215], v[224:227], v[0:15]
	v_add_u32_e32 v149, v149, v182
	v_add_u32_e32 v230, v192, v182
	ds_read_b128 v[204:207], v230 offset:32768
	ds_read_b128 v[208:211], v149
	ds_read_b128 v[212:215], v230 offset:36864
	ds_read_b128 v[216:219], v149 offset:4096
	ds_read_b128 v[220:223], v149 offset:8192
	ds_read_b128 v[224:227], v149 offset:12288
	s_waitcnt lgkmcnt(6)
	v_mfma_f32_32x32x16_bf16 v[112:127], v[154:157], v[158:161], v[112:127]
	v_mfma_f32_32x32x16_bf16 v[96:111], v[154:157], v[166:169], v[96:111]
	v_mfma_f32_32x32x16_bf16 v[80:95], v[154:157], v[170:173], v[80:95]
	v_mfma_f32_32x32x16_bf16 v[64:79], v[154:157], v[174:177], v[64:79]
	v_mfma_f32_32x32x16_bf16 v[48:63], v[162:165], v[158:161], v[48:63]
	v_mfma_f32_32x32x16_bf16 v[32:47], v[162:165], v[166:169], v[32:47]
	v_mfma_f32_32x32x16_bf16 v[16:31], v[162:165], v[170:173], v[16:31]
	v_mfma_f32_32x32x16_bf16 v[0:15], v[162:165], v[174:177], v[0:15]
	s_waitcnt vmcnt(0) lgkmcnt(0)
	s_barrier
	v_mfma_f32_32x32x16_bf16 v[112:127], v[204:207], v[208:211], v[112:127]
	v_mfma_f32_32x32x16_bf16 v[96:111], v[204:207], v[216:219], v[96:111]
	v_mfma_f32_32x32x16_bf16 v[80:95], v[204:207], v[220:223], v[80:95]
	v_mfma_f32_32x32x16_bf16 v[64:79], v[204:207], v[224:227], v[64:79]
	v_mfma_f32_32x32x16_bf16 v[48:63], v[212:215], v[208:211], v[48:63]
	v_mfma_f32_32x32x16_bf16 v[32:47], v[212:215], v[216:219], v[32:47]
	v_mfma_f32_32x32x16_bf16 v[16:31], v[212:215], v[220:223], v[16:31]
	v_mfma_f32_32x32x16_bf16 v[0:15], v[212:215], v[224:227], v[0:15]
	s_cbranch_scc0 .LBB0_1175
; #define GAS __attribute__((address_space(1)))
; #define MFMA(a, b, c) __builtin_amdgcn_mfma_f32_32x32x16_bf16((a), (b), (c), 0, 0, 0)
; #define G_BARRIER() { asm volatile("s_waitcnt vmcnt(0) lgkmcnt(0)" ::: "memory"); __builtin_amdgcn_s_barrier(); asm volatile("" ::: "memory"); }
;     ...
;         for (int kt = 0; kt < nk; ++kt) {
;             if (kt + 1 < nk) { G_DMA(kt + 1, (kt + 1) & 1); }
;             const unsigned char* sa = lds + (kt & 1) * 65536 + (wt * 32 * TB + r) * 128;
;             const unsigned char* sw = lds + (kt & 1) * 65536 + 32768 + (wf * 64 + r) * 128;
; #pragma unroll
;             for (int ks = 0; ks < 4; ++ks) {
;                 bf16x8 wfr[2], afr[TB];
; #pragma unroll
;                 for (int fb = 0; fb < 2; ++fb) wfr[fb] = *(const bf16x8*)(sw + fb * 4096 + koff[ks]);
; #pragma unroll
;                 for (int tb = 0; tb < TB; ++tb) afr[tb] = *(const bf16x8*)(sa + tb * 4096 + koff[ks]);
; #pragma unroll
;                 for (int fb = 0; fb < 2; ++fb)
; #pragma unroll
;                     for (int tb = 0; tb < TB; ++tb) acc[fb][tb] = MFMA(wfr[fb], afr[tb], acc[fb][tb]);
;             }
;             G_BARRIER();
;         }
;         const int un = u + nslots;
;         if (un < nloc) {
;             Ag = (const GAS bf16_t*)(A + (size_t)(xcd + nx * (un / Ntiles)) * RM * K) + dsrc; Wg = (const GAS bf16_t*)(Wt + (size_t)(un % Ntiles) * 256 * K) + dsrc;
;             G_DMA(0, 0);
;         }
	v_add_u32_e32 v149, v190, v179
	ds_read_b128 v[154:157], v149
	v_add_u32_e32 v170, v189, v179
	ds_read_b128 v[158:161], v170
	ds_read_b128 v[162:165], v170 offset:4096
	ds_read_b128 v[166:169], v170 offset:8192
	ds_read_b128 v[170:173], v170 offset:12288
	s_add_i32 s53, s54, s34
	s_cmp_ge_i32 s53, s35
	s_cselect_b64 s[42:43], -1, 0
	s_waitcnt lgkmcnt(0)
	v_mfma_f32_32x32x16_bf16 v[112:127], v[154:157], v[158:161], v[112:127]
	s_cmp_lt_i32 s53, s35
	v_mfma_f32_32x32x16_bf16 v[96:111], v[154:157], v[162:165], v[96:111]
	v_mfma_f32_32x32x16_bf16 v[80:95], v[154:157], v[166:169], v[80:95]
	v_mfma_f32_32x32x16_bf16 v[64:79], v[154:157], v[170:173], v[64:79]
	ds_read_b128 v[154:157], v149 offset:4096
	v_add_u32_e32 v149, v190, v180
	s_waitcnt lgkmcnt(0)
	v_mfma_f32_32x32x16_bf16 v[48:63], v[154:157], v[158:161], v[48:63]
	v_mfma_f32_32x32x16_bf16 v[32:47], v[154:157], v[162:165], v[32:47]
	v_mfma_f32_32x32x16_bf16 v[16:31], v[154:157], v[166:169], v[16:31]
	v_mfma_f32_32x32x16_bf16 v[0:15], v[154:157], v[170:173], v[0:15]
	ds_read_b128 v[154:157], v149
	v_add_u32_e32 v170, v189, v180
	ds_read_b128 v[158:161], v170
	ds_read_b128 v[162:165], v170 offset:4096
	ds_read_b128 v[166:169], v170 offset:8192
	ds_read_b128 v[170:173], v170 offset:12288
	s_waitcnt lgkmcnt(0)
	v_mfma_f32_32x32x16_bf16 v[112:127], v[154:157], v[158:161], v[112:127]
	v_mfma_f32_32x32x16_bf16 v[96:111], v[154:157], v[162:165], v[96:111]
	v_mfma_f32_32x32x16_bf16 v[80:95], v[154:157], v[166:169], v[80:95]
	v_mfma_f32_32x32x16_bf16 v[64:79], v[154:157], v[170:173], v[64:79]
	ds_read_b128 v[154:157], v149 offset:4096
	v_add_u32_e32 v149, v190, v181
	s_waitcnt lgkmcnt(0)
	v_mfma_f32_32x32x16_bf16 v[48:63], v[154:157], v[158:161], v[48:63]
	v_mfma_f32_32x32x16_bf16 v[32:47], v[154:157], v[162:165], v[32:47]
	v_mfma_f32_32x32x16_bf16 v[16:31], v[154:157], v[166:169], v[16:31]
	v_mfma_f32_32x32x16_bf16 v[0:15], v[154:157], v[170:173], v[0:15]
	ds_read_b128 v[154:157], v149
	v_add_u32_e32 v170, v189, v181
	ds_read_b128 v[158:161], v170
	ds_read_b128 v[162:165], v170 offset:4096
	ds_read_b128 v[166:169], v170 offset:8192
	ds_read_b128 v[170:173], v170 offset:12288
	s_waitcnt lgkmcnt(0)
	v_mfma_f32_32x32x16_bf16 v[112:127], v[154:157], v[158:161], v[112:127]
	v_mfma_f32_32x32x16_bf16 v[96:111], v[154:157], v[162:165], v[96:111]
	v_mfma_f32_32x32x16_bf16 v[80:95], v[154:157], v[166:169], v[80:95]
	v_mfma_f32_32x32x16_bf16 v[64:79], v[154:157], v[170:173], v[64:79]
	ds_read_b128 v[154:157], v149 offset:4096
	v_add_u32_e32 v149, v190, v182
	s_waitcnt lgkmcnt(0)
	v_mfma_f32_32x32x16_bf16 v[48:63], v[154:157], v[158:161], v[48:63]
	v_mfma_f32_32x32x16_bf16 v[32:47], v[154:157], v[162:165], v[32:47]
	v_mfma_f32_32x32x16_bf16 v[16:31], v[154:157], v[166:169], v[16:31]
	v_mfma_f32_32x32x16_bf16 v[0:15], v[154:157], v[170:173], v[0:15]
	ds_read_b128 v[154:157], v149
	v_add_u32_e32 v170, v189, v182
	ds_read_b128 v[158:161], v170
	ds_read_b128 v[162:165], v170 offset:4096
	ds_read_b128 v[166:169], v170 offset:8192
	ds_read_b128 v[170:173], v170 offset:12288
	s_waitcnt lgkmcnt(0)
	v_mfma_f32_32x32x16_bf16 v[112:127], v[154:157], v[158:161], v[112:127]
	v_mfma_f32_32x32x16_bf16 v[96:111], v[154:157], v[162:165], v[96:111]
	v_mfma_f32_32x32x16_bf16 v[80:95], v[154:157], v[166:169], v[80:95]
	v_mfma_f32_32x32x16_bf16 v[64:79], v[154:157], v[170:173], v[64:79]
	ds_read_b128 v[154:157], v149 offset:4096
	s_waitcnt vmcnt(0) lgkmcnt(0)
	s_barrier
	s_waitcnt lgkmcnt(0)
	v_mfma_f32_32x32x16_bf16 v[48:63], v[154:157], v[158:161], v[48:63]
	v_mfma_f32_32x32x16_bf16 v[32:47], v[154:157], v[162:165], v[32:47]
	v_mfma_f32_32x32x16_bf16 v[16:31], v[154:157], v[166:169], v[16:31]
	v_mfma_f32_32x32x16_bf16 v[0:15], v[154:157], v[170:173], v[0:15]
	s_cbranch_scc0 .LBB0_1173
	s_ashr_i32 s55, s53, 31
	s_lshr_b32 s55, s55, 30
	s_add_i32 s55, s53, s55
	s_ashr_i32 s56, s55, 2
	s_lshl_b32 s56, s56, s27
	s_add_i32 s56, s56, s33
	s_ashr_i32 s57, s56, 31
	s_lshl_b64 s[56:57], s[56:57], 19
	s_add_u32 s56, s1, s56
	s_addc_u32 s57, s3, s57
	s_and_b32 s55, s55, -4
	s_sub_i32 s58, s53, s55
	s_ashr_i32 s59, s58, 31
	s_lshl_b64 s[58:59], s[58:59], 19
	s_mov_b32 m0, s45
	v_mov_b32_e32 v149, v129
	s_add_u32 s58, s18, s58
	v_lshl_add_u64 v[150:151], s[56:57], 0, v[148:149]
	s_addc_u32 s59, s19, s59
	global_load_lds_dwordx4 v148, s[56:57]
	s_mov_b32 m0, s46
	v_lshl_add_u64 v[152:153], s[58:59], 0, v[148:149]
	global_load_lds_dwordx4 v148, s[58:59]
	v_lshl_add_u64 v[154:155], v[150:151], 0, s[14:15]
	s_mov_b32 m0, s47
	s_nop 0
	global_load_lds_dwordx4 v[154:155], off
	v_lshl_add_u64 v[154:155], v[152:153], 0, s[14:15]
	s_mov_b32 m0, s48
	s_nop 0
	global_load_lds_dwordx4 v[154:155], off
	v_lshl_add_u64 v[154:155], v[150:151], 0, s[16:17]
	s_mov_b32 m0, s49
	s_nop 0
	global_load_lds_dwordx4 v[154:155], off
	v_lshl_add_u64 v[154:155], v[152:153], 0, s[16:17]
	s_mov_b32 m0, s50
	s_nop 0
	global_load_lds_dwordx4 v[154:155], off
	v_lshl_add_u64 v[154:155], v[150:151], 0, s[20:21]
	s_mov_b32 m0, s51
	s_nop 0
	global_load_lds_dwordx4 v[154:155], off
	v_lshl_add_u64 v[154:155], v[152:153], 0, s[20:21]
	s_mov_b32 m0, s52
	s_nop 0
	global_load_lds_dwordx4 v[154:155], off
	s_branch .LBB0_1173
